# added: retention-in-proj (P6) epilogue row-rms prefetch (6 rows ahead + 2 late), retention chunk loop no longer drains stores before its top barrier
# speedup vs baseline: 1.0363x; 1.0073x over previous
; #define PG8_STAGE(bufoff, gbase, voff) do { _Pragma("unroll") for (int _i = 0; _i < 2; ++_i) \
;         __builtin_amdgcn_global_load_lds((const unsigned*)((const char*)(gbase) + (voff)[_i]), (PG8_LAS unsigned*)(lds + (bufoff) + ldsw + _i * 8192), 16, 0, 0); } while (0)
; #define PG8_WAIT_V(n) asm volatile("s_waitcnt vmcnt(" #n ")" ::: "memory")
; #define PG8_BAR __builtin_amdgcn_s_barrier()
; template <class Epi, class Sched, bool ALIGN_EPI = false, bool SP2 = false>
; __device__ __forceinline__ void gemm_phase(PG8_LAS unsigned char* lds, const Gemm g, const Sched& S, const Epi& E) {
;     ...
;     const char* cA = (const char*)g.A + (size_t)cur.pm * tstep + (size_t)cur.kt0 * kstep; const char* cB = (const char*)g.Bt + (size_t)cur.pn * tstep + (size_t)cur.kt0 * kstep;
;     S.a_ready(cur);
;     if constexpr (SP2) {
;         PG8_STAGE(PG8_SB(0, 0), cB, voffB); PG8_STAGE(PG8_SB(0, 1), cB + hstep, voffB); PG8_STAGE(PG8_SA(0, 0), cA, voffA); PG8_STAGE(PG8_SA(0, 1), cA + hstep, voffA);
;         if (wr == 1) PG8_BAR;
;         PG8_WAIT_V(2); PG8_BAR;
;         PG8_STAGE(PG8_SB(1, 0), cB + kstep, voffB); PG8_STAGE(PG8_SA(1, 0), cA + kstep, voffA); PG8_STAGE(PG8_SB(1, 1), cB + hstep + kstep, voffB);
;         PG8_WAIT_V(6); PG8_BAR;
; __device__ __forceinline__ float row_rs(const float* part, int row) {
;     const f32x4* p = (const f32x4*)(part + (size_t)row * 16);
;     const f32x4 a = p[0], b = p[1], c = p[2], d = p[3];
.LBB0_814:
	v_and_b32_e32 v246, 15, v146
	v_lshrrev_b32_e32 v214, 8, v146
	v_lshl_or_b32 v246, v214, 6, v246
	v_bfe_u32 v214, v146, 4, 2
	v_lshlrev_b32_e32 v214, 4, v214
	v_lshl_or_b32 v246, v246, 6, v214
	v_lshl_add_u32 v214, s8, 14, v246
	v_add_u32_e32 v215, 0x2000, v214
	global_load_dwordx4 v[230:233], v214, s[90:91]
	global_load_dwordx4 v[234:237], v214, s[90:91] offset:1024
	global_load_dwordx4 v[238:241], v214, s[90:91] offset:2048
	global_load_dwordx4 v[242:245], v214, s[90:91] offset:3072
	global_load_dwordx4 v[248:251], v215, s[90:91]
	global_load_dwordx4 v[252:255], v215, s[90:91] offset:1024
	s_add_u32 s48, s74, 0x2900000
	s_addc_u32 s49, s75, 0
	s_ashr_i32 s9, s8, 31
	s_lshl_b64 s[0:1], s[8:9], 19
	s_add_u32 s10, s88, s0
	s_addc_u32 s11, s89, s1
	s_ashr_i32 s7, s6, 31
	v_lshrrev_b32_e32 v4, 1, v146
	s_lshl_b64 s[0:1], s[6:7], 19
	v_and_b32_e32 v10, 24, v4
	v_lshrrev_b32_e32 v4, 5, v146
	s_add_u32 s38, s48, s0
	v_and_b32_e32 v4, 4, v4
	v_bfe_u32 v5, v146, 2, 2
	s_addc_u32 s39, s49, s1
	v_lshlrev_b32_e32 v1, 4, v146
	v_and_b32_e32 v2, 32, v146
	v_bfe_u32 v3, v146, 2, 4
	v_or3_b32 v4, v4, v5, v10
	v_lshrrev_b32_e32 v5, 3, v146
	s_movk_i32 s1, 0x70
	v_bitop3_b32 v2, v1, v2, 48 bitop3:0x6c
	v_and_or_b32 v6, v5, s1, v3
	s_movk_i32 s1, 0x60
	v_add_u32_e32 v1, 0x2000, v1
	v_and_or_b32 v5, v5, s1, v4
	v_lshrrev_b32_e32 v1, 7, v1
	s_movk_i32 s1, 0xf0
	v_and_or_b32 v3, v1, s1, v3
	s_movk_i32 s1, 0xe0
	v_and_or_b32 v1, v1, s1, v4
	s_lshr_b32 s1, s4, 6
	s_lshl_b32 s50, s1, 10
	v_and_or_b32 v2, v146, 64, v2
	s_add_i32 s51, s50, 0
	v_lshl_or_b32 v136, v5, 11, v2
	s_add_i32 m0, s51, 0x10000
	s_lshr_b32 s0, s4, 8
	global_load_lds_dwordx4 v136, s[38:39]
	s_add_i32 m0, s51, 0x12000
	v_lshl_or_b32 v140, v1, 11, v2
	s_add_u32 s2, s38, 0x40000
	global_load_lds_dwordx4 v140, s[38:39]
	s_addc_u32 s3, s39, 0
	s_add_i32 m0, s51, 0x14000
	s_add_i32 s52, s51, 0x2000
	global_load_lds_dwordx4 v136, s[2:3]
	s_add_i32 m0, s51, 0x16000
	v_lshl_or_b32 v134, v6, 11, v2
	global_load_lds_dwordx4 v140, s[2:3]
	s_mov_b32 m0, s51
	s_add_u32 s2, s10, 0x40000
	v_lshl_or_b32 v138, v3, 11, v2
	global_load_lds_dwordx4 v134, s[10:11]
	s_mov_b32 m0, s52
	s_addc_u32 s3, s11, 0
	s_add_i32 s53, s51, 0x4000
	global_load_lds_dwordx4 v138, s[10:11]
	s_mov_b32 m0, s53
	s_add_i32 s54, s51, 0x6000
	global_load_lds_dwordx4 v134, s[2:3]
	s_mov_b32 m0, s54
	v_mov_b32_e32 v143, 0
	global_load_lds_dwordx4 v138, s[2:3]
	v_mov_b32_e32 v137, v143
	v_mov_b32_e32 v141, v143
	v_mov_b32_e32 v135, v143
	v_mov_b32_e32 v139, v143
	s_cmp_eq_u32 s0, 1
	s_mov_b32 s17, 0
	v_lshl_add_u64 v[8:9], s[38:39], 0, v[136:137]
	v_lshl_add_u64 v[6:7], s[38:39], 0, v[140:141]
	v_lshl_add_u64 v[4:5], s[10:11], 0, v[134:135]
	v_lshl_add_u64 v[2:3], s[10:11], 0, v[138:139]
	s_cselect_b64 s[18:19], -1, 0
	s_cmp_lg_u32 s0, 1
	s_movk_i32 s55, 0x4000
	s_cbranch_scc1 .LBB0_816
	s_barrier

; __device__ __forceinline__ float row_rs(const float* part, int row) {
;     const f32x4* p = (const f32x4*)(part + (size_t)row * 16);
;     const f32x4 a = p[0], b = p[1], c = p[2], d = p[3];
;     __device__ __forceinline__ void operator()(const Acc& acc, const pg8::Unit& u, int wr, int wc, int fr, int fq) const {
;     ...
;             for (int m = 0; m < 4; ++m) {
;                 const int row = u.pm * 256 + ai * 128 + wr * 64 + m * 16 + fr;
;                 const float rs = row_rs(part, row);
;                 if (u.pn < 8) {
;                     const int pidx = row < TP ? (row & (SEQ - 1)) : SEQ + ((row - TP) & 3);
;                     const int i0 = wc * 32 + 8 * fq;
;                     const f32x4* cs = (const f32x4*)(rope + ((size_t)pidx * 128 + i0) * 2);
;                     const float sc = (u.pn < 4) ? rs : rs * 0.0625f;
;                     f32x4 o1[2], o2[2];
; #pragma unroll
;                     for (int n = 0; n < 2; ++n) { const f32x4 c01 = cs[2 * n], c23 = cs[2 * n + 1];
;                         const f32x4 x1 = acc[ai][0][m][n] * sc, x2 = acc[ai][1][m][n] * sc;
;                         const f32x4 cc = (f32x4){c01[0], c01[2], c23[0], c23[2]}, sn = (f32x4){c01[1], c01[3], c23[1], c23[3]};
;                         o1[n] = x1 * cc - x2 * sn; o2[n] = x1 * sn + x2 * cc; }
;                     bf16_t* dst = (u.pn < 4 ? Q : K) + (size_t)row * D + (u.pn & 3) * 256 + i0;
;                     *(u32x4*)dst = pack8(o1[0], o1[1]); *(u32x4*)(dst + 128) = pack8(o2[0], o2[1]);
;                 } else if (u.pn < 16) {
; #pragma unroll
;                     for (int bj = 0; bj < 2; ++bj) { const int col = (u.pn - 8) * 256 + bj * 128 + wc * 32 + 8 * fq;
;                         *(u32x4*)(V + (size_t)row * VD + col) = pack8(acc[ai][bj][m][0] * rs, acc[ai][bj][m][1] * rs); }
;                 } else {
; #pragma unroll
;                     for (int bj = 0; bj < 2; ++bj) { const int col = (u.pn - 16) * 256 + bj * 128 + wc * 32 + 8 * fq;
;                         f32x4 g[2];
; #pragma unroll
;                         for (int n = 0; n < 2; ++n)
; #pragma unroll
;                             for (int e = 0; e < 4; ++e) g[n][e] = silu_f(acc[ai][bj][m][n][e] * rs);
;                         *(u32x4*)(G + (size_t)row * VD + col) = pack8(g[0], g[1]); }
.LBB0_837:
	s_waitcnt vmcnt(8)
	v_lshl_add_u32 v214, s8, 14, v246
	v_add_u32_e32 v215, 0x2000, v214
	global_load_dwordx4 v[190:193], v215, s[90:91] offset:2048
	global_load_dwordx4 v[194:197], v215, s[90:91] offset:3072
	v_add_f32_e32 v230, v230, v231
	v_add_f32_e32 v232, v232, v233
	v_add_f32_e32 v234, v234, v235
	v_add_f32_e32 v236, v236, v237
	v_add_f32_e32 v238, v238, v239
	v_add_f32_e32 v240, v240, v241
	v_add_f32_e32 v242, v242, v243
	v_add_f32_e32 v244, v244, v245
	v_add_f32_e32 v248, v248, v249
	v_add_f32_e32 v250, v250, v251
	v_add_f32_e32 v252, v252, v253
	v_add_f32_e32 v254, v254, v255
	v_add_f32_e32 v198, v230, v232
	v_add_f32_e32 v199, v234, v236
	v_add_f32_e32 v200, v238, v240
	v_add_f32_e32 v201, v242, v244
	v_add_f32_e32 v202, v248, v250
	v_add_f32_e32 v203, v252, v254
	v_mov_b32_e32 v206, v198
	v_mov_b32_e32 v207, v199
	v_mov_b32_e32 v208, v200
	v_mov_b32_e32 v209, v201
	v_mov_b32_e32 v210, v202
	v_mov_b32_e32 v211, v203
	v_permlane16_swap_b32_e32 v198, v206
	v_permlane16_swap_b32_e32 v199, v207
	v_permlane16_swap_b32_e32 v200, v208
	v_permlane16_swap_b32_e32 v201, v209
	v_permlane16_swap_b32_e32 v202, v210
	v_permlane16_swap_b32_e32 v203, v211
	v_add_f32_e32 v198, v198, v206
	v_add_f32_e32 v199, v199, v207
	v_add_f32_e32 v200, v200, v208
	v_add_f32_e32 v201, v201, v209
	v_add_f32_e32 v202, v202, v210
	v_add_f32_e32 v203, v203, v211
	v_mov_b32_e32 v206, v198
	v_mov_b32_e32 v207, v199
	v_mov_b32_e32 v208, v200
	v_mov_b32_e32 v209, v201
	v_mov_b32_e32 v210, v202
	v_mov_b32_e32 v211, v203
	v_permlane32_swap_b32_e32 v198, v206
	v_permlane32_swap_b32_e32 v199, v207
	v_permlane32_swap_b32_e32 v200, v208
	v_permlane32_swap_b32_e32 v201, v209
	v_permlane32_swap_b32_e32 v202, v210
	v_permlane32_swap_b32_e32 v203, v211
	v_add_f32_e32 v198, v198, v206
	v_add_f32_e32 v199, v199, v207
	v_add_f32_e32 v200, v200, v208
	v_add_f32_e32 v201, v201, v209
	v_add_f32_e32 v202, v202, v210
	v_add_f32_e32 v203, v203, v211
	v_fmamk_f32 v198, v198, 0x3a800000, v171
	v_fmamk_f32 v199, v199, 0x3a800000, v171
	v_fmamk_f32 v200, v200, 0x3a800000, v171
	v_fmamk_f32 v201, v201, 0x3a800000, v171
	v_fmamk_f32 v202, v202, 0x3a800000, v171
	v_fmamk_f32 v203, v203, 0x3a800000, v171
	v_rsq_f32_e32 v198, v198
	v_rsq_f32_e32 v199, v199
	v_rsq_f32_e32 v200, v200
	v_rsq_f32_e32 v201, v201
	v_rsq_f32_e32 v202, v202
	v_rsq_f32_e32 v203, v203
	v_lshl_add_u32 v214, s30, 14, v246
	v_add_u32_e32 v215, 0x2000, v214
	global_load_dwordx4 v[230:233], v214, s[90:91]
	global_load_dwordx4 v[234:237], v214, s[90:91] offset:1024
	global_load_dwordx4 v[238:241], v214, s[90:91] offset:2048
	global_load_dwordx4 v[242:245], v214, s[90:91] offset:3072
	global_load_dwordx4 v[248:251], v215, s[90:91]
	global_load_dwordx4 v[252:255], v215, s[90:91] offset:1024
	v_lshl_add_u32 v160, s8, 8, v1
	v_ashrrev_i32_e32 v161, 31, v160
	v_lshlrev_b64 v[130:131], 6, v[160:161]
	v_lshl_add_u64 v[130:131], s[90:91], 0, v[130:131]
	s_cmp_gt_i32 s6, 7
	s_cselect_b64 s[38:39], -1, 0
	s_cmp_gt_u32 s6, 15
	s_cselect_b64 s[4:5], -1, 0
	s_lshl_b32 s16, s6, 8
	v_cndmask_b32_e64 v133, 0, 1, s[4:5]
	s_cmp_lt_i32 s6, 4
	v_cmp_ne_u32_e64 s[6:7], 1, v133
	s_cselect_b64 s[4:5], -1, 0
	s_and_b64 s[8:9], exec, s[38:39]
	s_mov_b64 s[10:11], -1
	v_add_u32_e32 v156, s16, v163
	v_add_u32_e32 v154, s16, v168
	s_nop 0
	s_nop 0
	s_nop 1
	s_nop 0
	v_mov_b32_e32 v162, v198
	s_mov_b64 vcc, s[8:9]
	s_cbranch_vccz .LBB0_843
	s_mov_b64 s[8:9], -1
	s_and_b64 vcc, exec, s[6:7]
	v_lshlrev_b64 v[158:159], 12, v[160:161]
	s_cbranch_vccnz .LBB0_840
	v_pk_mul_f32 v[164:165], v[128:129], v[162:163] op_sel_hi:[1,0]
	v_pk_mul_f32 v[172:173], v[122:123], v[162:163] op_sel_hi:[1,0]
	v_mul_f32_e32 v142, 0xbfb8aa3b, v164
	v_exp_f32_e32 v142, v142
	v_mul_f32_e32 v155, 0xbfb8aa3b, v165
	v_exp_f32_e32 v155, v155
	v_mul_f32_e32 v157, 0xbfb8aa3b, v173
	v_add_f32_e32 v142, 1.0, v142
	v_rcp_f32_e32 v166, v142
	v_add_f32_e32 v142, 1.0, v155
	v_mul_f32_e32 v155, 0xbfb8aa3b, v172
	v_exp_f32_e32 v155, v155
	v_exp_f32_e32 v157, v157
	v_pk_mul_f32 v[176:177], v[124:125], v[162:163] op_sel_hi:[1,0]
	v_pk_mul_f32 v[130:131], v[126:127], v[162:163] op_sel_hi:[1,0]
	v_rcp_f32_e32 v167, v142
	v_add_f32_e32 v142, 1.0, v155
	v_mul_f32_e32 v155, 0xbfb8aa3b, v176
	v_mul_f32_e32 v132, 0xbfb8aa3b, v130
	v_mul_f32_e32 v133, 0xbfb8aa3b, v131
	v_rcp_f32_e32 v174, v142
	v_add_f32_e32 v142, 1.0, v157
	v_exp_f32_e32 v155, v155
	v_mul_f32_e32 v157, 0xbfb8aa3b, v177
	v_exp_f32_e32 v132, v132
	v_exp_f32_e32 v133, v133
	v_exp_f32_e32 v157, v157
	v_rcp_f32_e32 v175, v142
	v_add_f32_e32 v142, 1.0, v155
	v_add_f32_e32 v132, 1.0, v132
	v_add_f32_e32 v133, 1.0, v133
	v_rcp_f32_e32 v178, v142
	v_add_f32_e32 v142, 1.0, v157
	v_rcp_f32_e32 v132, v132
	v_rcp_f32_e32 v133, v133
	v_rcp_f32_e32 v179, v142
	v_ashrrev_i32_e32 v157, 31, v156
	s_mov_b64 s[8:9], 0
	v_pk_mul_f32 v[130:131], v[130:131], v[132:133]
	v_pk_mul_f32 v[132:133], v[164:165], v[166:167]
	v_pk_mul_f32 v[166:167], v[176:177], v[178:179]
	v_cvt_pk_bf16_f32 v130, v130, v131
	v_cvt_pk_bf16_f32 v131, v132, v133
	v_cvt_pk_bf16_f32 v133, v166, v167
	v_pk_mul_f32 v[166:167], v[118:119], v[162:163] op_sel_hi:[1,0]
	v_pk_mul_f32 v[164:165], v[172:173], v[174:175]
	v_mul_f32_e32 v142, 0xbfb8aa3b, v166
	v_exp_f32_e32 v142, v142
	v_mul_f32_e32 v155, 0xbfb8aa3b, v167
	v_cvt_pk_bf16_f32 v132, v164, v165
	v_lshl_add_u64 v[164:165], s[22:23], 0, v[158:159]
	v_exp_f32_e32 v155, v155
	v_lshl_add_u64 v[164:165], v[156:157], 1, v[164:165]
	global_store_dwordx4 v[164:165], v[130:133], off
	v_pk_mul_f32 v[174:175], v[114:115], v[162:163] op_sel_hi:[1,0]
	v_pk_mul_f32 v[178:179], v[116:117], v[162:163] op_sel_hi:[1,0]
	v_pk_mul_f32 v[132:133], v[120:121], v[162:163] op_sel_hi:[1,0]
	v_add_f32_e32 v130, 1.0, v142
	v_mul_f32_e32 v142, 0xbfb8aa3b, v132
	v_add_f32_e32 v131, 1.0, v155
	v_exp_f32_e32 v142, v142
	v_mul_f32_e32 v155, 0xbfb8aa3b, v133
	v_exp_f32_e32 v155, v155
	v_mul_f32_e32 v157, 0xbfb8aa3b, v175
	v_add_f32_e32 v142, 1.0, v142
	v_rcp_f32_e32 v172, v142
	v_add_f32_e32 v142, 1.0, v155
	v_mul_f32_e32 v155, 0xbfb8aa3b, v174
	v_exp_f32_e32 v155, v155
	v_exp_f32_e32 v157, v157
	v_rcp_f32_e32 v173, v142
	v_rcp_f32_e32 v130, v130
	v_add_f32_e32 v142, 1.0, v155
	v_mul_f32_e32 v155, 0xbfb8aa3b, v178
	v_rcp_f32_e32 v176, v142
	v_add_f32_e32 v142, 1.0, v157
	v_exp_f32_e32 v155, v155
	v_mul_f32_e32 v157, 0xbfb8aa3b, v179
	v_exp_f32_e32 v157, v157
	v_rcp_f32_e32 v177, v142
	v_add_f32_e32 v142, 1.0, v155
	v_rcp_f32_e32 v131, v131
	v_rcp_f32_e32 v180, v142
	v_add_f32_e32 v142, 1.0, v157
	v_rcp_f32_e32 v181, v142
	v_pk_mul_f32 v[130:131], v[166:167], v[130:131]
	v_pk_mul_f32 v[132:133], v[132:133], v[172:173]
	v_pk_mul_f32 v[172:173], v[174:175], v[176:177]
	v_pk_mul_f32 v[166:167], v[178:179], v[180:181]
	v_cvt_pk_bf16_f32 v130, v130, v131
	v_cvt_pk_bf16_f32 v131, v132, v133
	v_cvt_pk_bf16_f32 v132, v172, v173

; __device__ __forceinline__ float silu_f(float x) { return x * __builtin_amdgcn_rcpf(1.0f + __expf(-x)); }
;     __device__ __forceinline__ void operator()(const Acc& acc, const pg8::Unit& u, int wr, int wc, int fr, int fq) const {
;     ...
;             for (int m = 0; m < 4; ++m) {
;                 const int row = u.pm * 256 + ai * 128 + wr * 64 + m * 16 + fr;
;                 const float rs = row_rs(part, row);
;                 if (u.pn < 8) {
;                     const int pidx = row < TP ? (row & (SEQ - 1)) : SEQ + ((row - TP) & 3);
;                     const int i0 = wc * 32 + 8 * fq;
;                     const f32x4* cs = (const f32x4*)(rope + ((size_t)pidx * 128 + i0) * 2);
;                     const float sc = (u.pn < 4) ? rs : rs * 0.0625f;
;                     f32x4 o1[2], o2[2];
; #pragma unroll
;                     for (int n = 0; n < 2; ++n) { const f32x4 c01 = cs[2 * n], c23 = cs[2 * n + 1];
;                         const f32x4 x1 = acc[ai][0][m][n] * sc, x2 = acc[ai][1][m][n] * sc;
;                         const f32x4 cc = (f32x4){c01[0], c01[2], c23[0], c23[2]}, sn = (f32x4){c01[1], c01[3], c23[1], c23[3]};
;                         o1[n] = x1 * cc - x2 * sn; o2[n] = x1 * sn + x2 * cc; }
;                     bf16_t* dst = (u.pn < 4 ? Q : K) + (size_t)row * D + (u.pn & 3) * 256 + i0;
;                     *(u32x4*)dst = pack8(o1[0], o1[1]); *(u32x4*)(dst + 128) = pack8(o2[0], o2[1]);
;                 } else if (u.pn < 16) {
; #pragma unroll
;                     for (int bj = 0; bj < 2; ++bj) { const int col = (u.pn - 8) * 256 + bj * 128 + wc * 32 + 8 * fq;
;                         *(u32x4*)(V + (size_t)row * VD + col) = pack8(acc[ai][bj][m][0] * rs, acc[ai][bj][m][1] * rs); }
;                 } else {
; #pragma unroll
;                     for (int bj = 0; bj < 2; ++bj) { const int col = (u.pn - 16) * 256 + bj * 128 + wc * 32 + 8 * fq;
;                         f32x4 g[2];
; #pragma unroll
;                         for (int n = 0; n < 2; ++n)
; #pragma unroll
;                             for (int e = 0; e < 4; ++e) g[n][e] = silu_f(acc[ai][bj][m][n][e] * rs);
;                         *(u32x4*)(G + (size_t)row * VD + col) = pack8(g[0], g[1]); }
.LBB0_845:
	v_or_b32_e32 v118, 16, v160
	v_ashrrev_i32_e32 v119, 31, v118
	v_cvt_pk_bf16_f32 v133, v166, v167
	v_lshlrev_b64 v[114:115], 6, v[118:119]
	global_store_dwordx4 v[164:165], v[130:133], off offset:256
	v_lshl_add_u64 v[128:129], s[90:91], 0, v[114:115]
	s_nop 0
	s_andn2_b64 vcc, exec, s[38:39]
	s_nop 0
	s_nop 0
	s_nop 1
	v_cndmask_b32_e64 v115, 0, 1, s[38:39]
	v_cmp_ne_u32_e64 s[8:9], 1, v115
	v_mov_b32_e32 v120, v199
	s_mov_b64 s[10:11], -1
	s_cbranch_vccnz .LBB0_851
	s_and_b64 vcc, exec, s[6:7]
	v_lshlrev_b64 v[124:125], 12, v[118:119]
	s_cbranch_vccnz .LBB0_848
	v_pk_mul_f32 v[122:123], v[112:113], v[120:121] op_sel_hi:[1,0]
	v_pk_mul_f32 v[114:115], v[110:111], v[120:121] op_sel_hi:[1,0]
	v_mul_f32_e32 v121, 0xbfb8aa3b, v122
	v_exp_f32_e32 v121, v121
	v_mul_f32_e32 v126, 0xbfb8aa3b, v123
	v_exp_f32_e32 v127, v126
	v_mul_f32_e32 v116, 0xbfb8aa3b, v114
	v_add_f32_e32 v121, 1.0, v121
	v_rcp_f32_e32 v126, v121
	v_add_f32_e32 v121, 1.0, v127
	v_pk_mul_f32 v[128:129], v[106:107], v[120:121] op_sel_hi:[1,0]
	v_mul_f32_e32 v117, 0xbfb8aa3b, v115
	v_mul_f32_e32 v127, 0xbfb8aa3b, v128
	v_exp_f32_e32 v130, v127
	v_mul_f32_e32 v127, 0xbfb8aa3b, v129
	v_exp_f32_e32 v131, v127
	v_rcp_f32_e32 v127, v121
	v_add_f32_e32 v121, 1.0, v130
	v_rcp_f32_e32 v130, v121
	v_add_f32_e32 v121, 1.0, v131
	v_pk_mul_f32 v[132:133], v[108:109], v[120:121] op_sel_hi:[1,0]
	v_exp_f32_e32 v116, v116
	v_mul_f32_e32 v131, 0xbfb8aa3b, v132
	v_exp_f32_e32 v142, v131
	v_mul_f32_e32 v131, 0xbfb8aa3b, v133
	v_exp_f32_e32 v117, v117
	v_exp_f32_e32 v155, v131
	v_rcp_f32_e32 v131, v121
	v_add_f32_e32 v121, 1.0, v142
	v_add_f32_e32 v116, 1.0, v116
	v_add_f32_e32 v117, 1.0, v117
	v_rcp_f32_e32 v164, v121
	v_add_f32_e32 v121, 1.0, v155
	v_rcp_f32_e32 v116, v116
	v_rcp_f32_e32 v117, v117
	v_rcp_f32_e32 v165, v121
	v_ashrrev_i32_e32 v157, 31, v156
	s_mov_b64 s[10:11], 0
	v_pk_mul_f32 v[114:115], v[114:115], v[116:117]
	v_pk_mul_f32 v[116:117], v[122:123], v[126:127]
	v_pk_mul_f32 v[126:127], v[132:133], v[164:165]
	v_cvt_pk_bf16_f32 v114, v114, v115
	v_cvt_pk_bf16_f32 v115, v116, v117
	v_cvt_pk_bf16_f32 v117, v126, v127
	v_pk_mul_f32 v[126:127], v[102:103], v[120:121] op_sel_hi:[1,0]
	v_pk_mul_f32 v[122:123], v[128:129], v[130:131]
	v_mul_f32_e32 v121, 0xbfb8aa3b, v126
	v_exp_f32_e32 v121, v121
	v_mul_f32_e32 v128, 0xbfb8aa3b, v127
	v_cvt_pk_bf16_f32 v116, v122, v123
	v_lshl_add_u64 v[122:123], s[22:23], 0, v[124:125]
	v_exp_f32_e32 v128, v128
	v_lshl_add_u64 v[122:123], v[156:157], 1, v[122:123]
	global_store_dwordx4 v[122:123], v[114:117], off
	s_nop 1
	v_pk_mul_f32 v[116:117], v[104:105], v[120:121] op_sel_hi:[1,0]
	v_add_f32_e32 v114, 1.0, v121
	v_mul_f32_e32 v121, 0xbfb8aa3b, v116
	v_add_f32_e32 v115, 1.0, v128
	v_exp_f32_e32 v121, v121
	v_mul_f32_e32 v128, 0xbfb8aa3b, v117
	v_exp_f32_e32 v129, v128
	v_rcp_f32_e32 v114, v114
	v_add_f32_e32 v121, 1.0, v121
	v_rcp_f32_e32 v128, v121
	v_add_f32_e32 v121, 1.0, v129
	v_pk_mul_f32 v[130:131], v[98:99], v[120:121] op_sel_hi:[1,0]
	v_rcp_f32_e32 v115, v115
	v_mul_f32_e32 v129, 0xbfb8aa3b, v130
	v_exp_f32_e32 v132, v129
	v_mul_f32_e32 v129, 0xbfb8aa3b, v131
	v_exp_f32_e32 v133, v129
	v_rcp_f32_e32 v129, v121
	v_add_f32_e32 v121, 1.0, v132
	v_rcp_f32_e32 v132, v121
	v_add_f32_e32 v121, 1.0, v133
	v_pk_mul_f32 v[164:165], v[100:101], v[120:121] op_sel_hi:[1,0]
	v_pk_mul_f32 v[114:115], v[126:127], v[114:115]
	v_mul_f32_e32 v133, 0xbfb8aa3b, v164
	v_exp_f32_e32 v142, v133
	v_mul_f32_e32 v133, 0xbfb8aa3b, v165
	v_exp_f32_e32 v155, v133
	v_rcp_f32_e32 v133, v121
	v_add_f32_e32 v121, 1.0, v142
	v_rcp_f32_e32 v166, v121
	v_add_f32_e32 v121, 1.0, v155
	v_rcp_f32_e32 v167, v121
	v_pk_mul_f32 v[116:117], v[116:117], v[128:129]
	v_pk_mul_f32 v[128:129], v[130:131], v[132:133]
	v_cvt_pk_bf16_f32 v114, v114, v115
	v_pk_mul_f32 v[126:127], v[164:165], v[166:167]
	v_cvt_pk_bf16_f32 v115, v116, v117
	v_cvt_pk_bf16_f32 v116, v128, v129

; __device__ __forceinline__ float silu_f(float x) { return x * __builtin_amdgcn_rcpf(1.0f + __expf(-x)); }
;     __device__ __forceinline__ void operator()(const Acc& acc, const pg8::Unit& u, int wr, int wc, int fr, int fq) const {
;     ...
;             for (int m = 0; m < 4; ++m) {
;                 const int row = u.pm * 256 + ai * 128 + wr * 64 + m * 16 + fr;
;                 const float rs = row_rs(part, row);
;                 if (u.pn < 8) {
;                     const int pidx = row < TP ? (row & (SEQ - 1)) : SEQ + ((row - TP) & 3);
;                     const int i0 = wc * 32 + 8 * fq;
;                     const f32x4* cs = (const f32x4*)(rope + ((size_t)pidx * 128 + i0) * 2);
;                     const float sc = (u.pn < 4) ? rs : rs * 0.0625f;
;                     f32x4 o1[2], o2[2];
; #pragma unroll
;                     for (int n = 0; n < 2; ++n) { const f32x4 c01 = cs[2 * n], c23 = cs[2 * n + 1];
;                         const f32x4 x1 = acc[ai][0][m][n] * sc, x2 = acc[ai][1][m][n] * sc;
;                         const f32x4 cc = (f32x4){c01[0], c01[2], c23[0], c23[2]}, sn = (f32x4){c01[1], c01[3], c23[1], c23[3]};
;                         o1[n] = x1 * cc - x2 * sn; o2[n] = x1 * sn + x2 * cc; }
;                     bf16_t* dst = (u.pn < 4 ? Q : K) + (size_t)row * D + (u.pn & 3) * 256 + i0;
;                     *(u32x4*)dst = pack8(o1[0], o1[1]); *(u32x4*)(dst + 128) = pack8(o2[0], o2[1]);
;                 } else if (u.pn < 16) {
; #pragma unroll
;                     for (int bj = 0; bj < 2; ++bj) { const int col = (u.pn - 8) * 256 + bj * 128 + wc * 32 + 8 * fq;
;                         *(u32x4*)(V + (size_t)row * VD + col) = pack8(acc[ai][bj][m][0] * rs, acc[ai][bj][m][1] * rs); }
;                 } else {
; #pragma unroll
;                     for (int bj = 0; bj < 2; ++bj) { const int col = (u.pn - 16) * 256 + bj * 128 + wc * 32 + 8 * fq;
;                         f32x4 g[2];
; #pragma unroll
;                         for (int n = 0; n < 2; ++n)
; #pragma unroll
;                             for (int e = 0; e < 4; ++e) g[n][e] = silu_f(acc[ai][bj][m][n][e] * rs);
;                         *(u32x4*)(G + (size_t)row * VD + col) = pack8(g[0], g[1]); }
.LBB0_853:
	v_or_b32_e32 v102, 32, v160
	v_ashrrev_i32_e32 v103, 31, v102
	v_cvt_pk_bf16_f32 v117, v126, v127
	v_lshlrev_b64 v[98:99], 6, v[102:103]
	global_store_dwordx4 v[122:123], v[114:117], off offset:256
	v_lshl_add_u64 v[112:113], s[90:91], 0, v[98:99]
	s_nop 0
	s_and_b64 vcc, exec, s[8:9]
	s_nop 0
	s_nop 0
	s_nop 1
	s_nop 0
	v_mov_b32_e32 v104, v200
	s_mov_b64 s[10:11], -1
	s_cbranch_vccnz .LBB0_859
	s_and_b64 vcc, exec, s[6:7]
	v_lshlrev_b64 v[108:109], 12, v[102:103]
	s_cbranch_vccnz .LBB0_856
	v_pk_mul_f32 v[106:107], v[96:97], v[104:105] op_sel_hi:[1,0]
	v_pk_mul_f32 v[98:99], v[94:95], v[104:105] op_sel_hi:[1,0]
	v_mul_f32_e32 v105, 0xbfb8aa3b, v106
	v_exp_f32_e32 v105, v105
	v_mul_f32_e32 v110, 0xbfb8aa3b, v107
	v_exp_f32_e32 v111, v110
	v_mul_f32_e32 v100, 0xbfb8aa3b, v98
	v_add_f32_e32 v105, 1.0, v105
	v_rcp_f32_e32 v110, v105
	v_add_f32_e32 v105, 1.0, v111
	v_pk_mul_f32 v[112:113], v[90:91], v[104:105] op_sel_hi:[1,0]
	v_mul_f32_e32 v101, 0xbfb8aa3b, v99
	v_mul_f32_e32 v111, 0xbfb8aa3b, v112
	v_exp_f32_e32 v114, v111
	v_mul_f32_e32 v111, 0xbfb8aa3b, v113
	v_exp_f32_e32 v115, v111
	v_rcp_f32_e32 v111, v105
	v_add_f32_e32 v105, 1.0, v114
	v_rcp_f32_e32 v114, v105
	v_add_f32_e32 v105, 1.0, v115
	v_pk_mul_f32 v[116:117], v[92:93], v[104:105] op_sel_hi:[1,0]
	v_exp_f32_e32 v100, v100
	v_mul_f32_e32 v115, 0xbfb8aa3b, v116
	v_exp_f32_e32 v118, v115
	v_mul_f32_e32 v115, 0xbfb8aa3b, v117
	v_exp_f32_e32 v101, v101
	v_exp_f32_e32 v119, v115
	v_rcp_f32_e32 v115, v105
	v_add_f32_e32 v105, 1.0, v118
	v_add_f32_e32 v100, 1.0, v100
	v_add_f32_e32 v101, 1.0, v101
	v_rcp_f32_e32 v118, v105
	v_add_f32_e32 v105, 1.0, v119
	v_rcp_f32_e32 v100, v100
	v_rcp_f32_e32 v101, v101
	v_rcp_f32_e32 v119, v105
	v_ashrrev_i32_e32 v157, 31, v156
	s_mov_b64 s[10:11], 0
	v_pk_mul_f32 v[98:99], v[98:99], v[100:101]
	v_pk_mul_f32 v[100:101], v[106:107], v[110:111]
	v_pk_mul_f32 v[110:111], v[116:117], v[118:119]
	v_cvt_pk_bf16_f32 v98, v98, v99
	v_cvt_pk_bf16_f32 v99, v100, v101
	v_cvt_pk_bf16_f32 v101, v110, v111
	v_pk_mul_f32 v[110:111], v[86:87], v[104:105] op_sel_hi:[1,0]
	v_pk_mul_f32 v[106:107], v[112:113], v[114:115]
	v_mul_f32_e32 v105, 0xbfb8aa3b, v110
	v_exp_f32_e32 v105, v105
	v_mul_f32_e32 v112, 0xbfb8aa3b, v111
	v_cvt_pk_bf16_f32 v100, v106, v107
	v_lshl_add_u64 v[106:107], s[22:23], 0, v[108:109]
	v_exp_f32_e32 v112, v112
	v_lshl_add_u64 v[106:107], v[156:157], 1, v[106:107]
	global_store_dwordx4 v[106:107], v[98:101], off
	s_nop 1
	v_pk_mul_f32 v[100:101], v[88:89], v[104:105] op_sel_hi:[1,0]
	v_add_f32_e32 v98, 1.0, v105
	v_mul_f32_e32 v105, 0xbfb8aa3b, v100
	v_add_f32_e32 v99, 1.0, v112
	v_exp_f32_e32 v105, v105
	v_mul_f32_e32 v112, 0xbfb8aa3b, v101
	v_exp_f32_e32 v113, v112
	v_rcp_f32_e32 v98, v98
	v_add_f32_e32 v105, 1.0, v105
	v_rcp_f32_e32 v112, v105
	v_add_f32_e32 v105, 1.0, v113
	v_pk_mul_f32 v[114:115], v[82:83], v[104:105] op_sel_hi:[1,0]
	v_rcp_f32_e32 v99, v99
	v_mul_f32_e32 v113, 0xbfb8aa3b, v114
	v_exp_f32_e32 v116, v113
	v_mul_f32_e32 v113, 0xbfb8aa3b, v115
	v_exp_f32_e32 v117, v113
	v_rcp_f32_e32 v113, v105
	v_add_f32_e32 v105, 1.0, v116
	v_rcp_f32_e32 v116, v105
	v_add_f32_e32 v105, 1.0, v117
	v_pk_mul_f32 v[118:119], v[84:85], v[104:105] op_sel_hi:[1,0]
	v_pk_mul_f32 v[98:99], v[110:111], v[98:99]
	v_mul_f32_e32 v117, 0xbfb8aa3b, v118
	v_exp_f32_e32 v120, v117
	v_mul_f32_e32 v117, 0xbfb8aa3b, v119
	v_exp_f32_e32 v121, v117
	v_rcp_f32_e32 v117, v105
	v_add_f32_e32 v105, 1.0, v120
	v_rcp_f32_e32 v120, v105
	v_add_f32_e32 v105, 1.0, v121
	v_rcp_f32_e32 v121, v105
	v_pk_mul_f32 v[100:101], v[100:101], v[112:113]
	v_pk_mul_f32 v[112:113], v[114:115], v[116:117]
	v_cvt_pk_bf16_f32 v98, v98, v99
	v_pk_mul_f32 v[110:111], v[118:119], v[120:121]
	v_cvt_pk_bf16_f32 v99, v100, v101
	v_cvt_pk_bf16_f32 v100, v112, v113

; __device__ __forceinline__ float silu_f(float x) { return x * __builtin_amdgcn_rcpf(1.0f + __expf(-x)); }
;     __device__ __forceinline__ void operator()(const Acc& acc, const pg8::Unit& u, int wr, int wc, int fr, int fq) const {
;     ...
;             for (int m = 0; m < 4; ++m) {
;                 const int row = u.pm * 256 + ai * 128 + wr * 64 + m * 16 + fr;
;                 const float rs = row_rs(part, row);
;                 if (u.pn < 8) {
;                     const int pidx = row < TP ? (row & (SEQ - 1)) : SEQ + ((row - TP) & 3);
;                     const int i0 = wc * 32 + 8 * fq;
;                     const f32x4* cs = (const f32x4*)(rope + ((size_t)pidx * 128 + i0) * 2);
;                     const float sc = (u.pn < 4) ? rs : rs * 0.0625f;
;                     f32x4 o1[2], o2[2];
; #pragma unroll
;                     for (int n = 0; n < 2; ++n) { const f32x4 c01 = cs[2 * n], c23 = cs[2 * n + 1];
;                         const f32x4 x1 = acc[ai][0][m][n] * sc, x2 = acc[ai][1][m][n] * sc;
;                         const f32x4 cc = (f32x4){c01[0], c01[2], c23[0], c23[2]}, sn = (f32x4){c01[1], c01[3], c23[1], c23[3]};
;                         o1[n] = x1 * cc - x2 * sn; o2[n] = x1 * sn + x2 * cc; }
;                     bf16_t* dst = (u.pn < 4 ? Q : K) + (size_t)row * D + (u.pn & 3) * 256 + i0;
;                     *(u32x4*)dst = pack8(o1[0], o1[1]); *(u32x4*)(dst + 128) = pack8(o2[0], o2[1]);
;                 } else if (u.pn < 16) {
; #pragma unroll
;                     for (int bj = 0; bj < 2; ++bj) { const int col = (u.pn - 8) * 256 + bj * 128 + wc * 32 + 8 * fq;
;                         *(u32x4*)(V + (size_t)row * VD + col) = pack8(acc[ai][bj][m][0] * rs, acc[ai][bj][m][1] * rs); }
;                 } else {
; #pragma unroll
;                     for (int bj = 0; bj < 2; ++bj) { const int col = (u.pn - 16) * 256 + bj * 128 + wc * 32 + 8 * fq;
;                         f32x4 g[2];
; #pragma unroll
;                         for (int n = 0; n < 2; ++n)
; #pragma unroll
;                             for (int e = 0; e < 4; ++e) g[n][e] = silu_f(acc[ai][bj][m][n][e] * rs);
;                         *(u32x4*)(G + (size_t)row * VD + col) = pack8(g[0], g[1]); }
.LBB0_861:
	v_or_b32_e32 v86, 48, v160
	v_ashrrev_i32_e32 v87, 31, v86
	v_cvt_pk_bf16_f32 v101, v110, v111
	v_lshlrev_b64 v[82:83], 6, v[86:87]
	global_store_dwordx4 v[106:107], v[98:101], off offset:256
	v_lshl_add_u64 v[96:97], s[90:91], 0, v[82:83]
	s_nop 0
	s_and_b64 vcc, exec, s[8:9]
	s_nop 0
	s_nop 0
	s_nop 1
	s_nop 0
	v_mov_b32_e32 v88, v201
	s_mov_b64 s[10:11], -1
	s_cbranch_vccnz .LBB0_867
	s_and_b64 vcc, exec, s[6:7]
	v_lshlrev_b64 v[92:93], 12, v[86:87]
	s_cbranch_vccnz .LBB0_864
	v_pk_mul_f32 v[90:91], v[80:81], v[88:89] op_sel_hi:[1,0]
	v_pk_mul_f32 v[82:83], v[78:79], v[88:89] op_sel_hi:[1,0]
	v_mul_f32_e32 v89, 0xbfb8aa3b, v90
	v_exp_f32_e32 v89, v89
	v_mul_f32_e32 v94, 0xbfb8aa3b, v91
	v_exp_f32_e32 v95, v94
	v_mul_f32_e32 v84, 0xbfb8aa3b, v82
	v_add_f32_e32 v89, 1.0, v89
	v_rcp_f32_e32 v94, v89
	v_add_f32_e32 v89, 1.0, v95
	v_pk_mul_f32 v[96:97], v[74:75], v[88:89] op_sel_hi:[1,0]
	v_mul_f32_e32 v85, 0xbfb8aa3b, v83
	v_mul_f32_e32 v95, 0xbfb8aa3b, v96
	v_exp_f32_e32 v98, v95
	v_mul_f32_e32 v95, 0xbfb8aa3b, v97
	v_exp_f32_e32 v99, v95
	v_rcp_f32_e32 v95, v89
	v_add_f32_e32 v89, 1.0, v98
	v_rcp_f32_e32 v98, v89
	v_add_f32_e32 v89, 1.0, v99
	v_pk_mul_f32 v[100:101], v[76:77], v[88:89] op_sel_hi:[1,0]
	v_exp_f32_e32 v84, v84
	v_mul_f32_e32 v99, 0xbfb8aa3b, v100
	v_exp_f32_e32 v102, v99
	v_mul_f32_e32 v99, 0xbfb8aa3b, v101
	v_exp_f32_e32 v85, v85
	v_exp_f32_e32 v103, v99
	v_rcp_f32_e32 v99, v89
	v_add_f32_e32 v89, 1.0, v102
	v_add_f32_e32 v84, 1.0, v84
	v_add_f32_e32 v85, 1.0, v85
	v_rcp_f32_e32 v102, v89
	v_add_f32_e32 v89, 1.0, v103
	v_rcp_f32_e32 v84, v84
	v_rcp_f32_e32 v85, v85
	v_rcp_f32_e32 v103, v89
	v_ashrrev_i32_e32 v157, 31, v156
	s_mov_b64 s[10:11], 0
	v_pk_mul_f32 v[82:83], v[82:83], v[84:85]
	v_pk_mul_f32 v[84:85], v[90:91], v[94:95]
	v_pk_mul_f32 v[94:95], v[100:101], v[102:103]
	v_cvt_pk_bf16_f32 v82, v82, v83
	v_cvt_pk_bf16_f32 v83, v84, v85
	v_cvt_pk_bf16_f32 v85, v94, v95
	v_pk_mul_f32 v[94:95], v[70:71], v[88:89] op_sel_hi:[1,0]
	v_pk_mul_f32 v[90:91], v[96:97], v[98:99]
	v_mul_f32_e32 v89, 0xbfb8aa3b, v94
	v_exp_f32_e32 v89, v89
	v_mul_f32_e32 v96, 0xbfb8aa3b, v95
	v_cvt_pk_bf16_f32 v84, v90, v91
	v_lshl_add_u64 v[90:91], s[22:23], 0, v[92:93]
	v_exp_f32_e32 v96, v96
	v_lshl_add_u64 v[90:91], v[156:157], 1, v[90:91]
	global_store_dwordx4 v[90:91], v[82:85], off
	s_nop 1
	v_pk_mul_f32 v[84:85], v[72:73], v[88:89] op_sel_hi:[1,0]
	v_add_f32_e32 v82, 1.0, v89
	v_mul_f32_e32 v89, 0xbfb8aa3b, v84
	v_add_f32_e32 v83, 1.0, v96
	v_exp_f32_e32 v89, v89
	v_mul_f32_e32 v96, 0xbfb8aa3b, v85
	v_exp_f32_e32 v97, v96
	v_rcp_f32_e32 v82, v82
	v_add_f32_e32 v89, 1.0, v89
	v_rcp_f32_e32 v96, v89
	v_add_f32_e32 v89, 1.0, v97
	v_pk_mul_f32 v[98:99], v[66:67], v[88:89] op_sel_hi:[1,0]
	v_rcp_f32_e32 v83, v83
	v_mul_f32_e32 v97, 0xbfb8aa3b, v98
	v_exp_f32_e32 v100, v97
	v_mul_f32_e32 v97, 0xbfb8aa3b, v99
	v_exp_f32_e32 v101, v97
	v_rcp_f32_e32 v97, v89
	v_add_f32_e32 v89, 1.0, v100
	v_rcp_f32_e32 v100, v89
	v_add_f32_e32 v89, 1.0, v101
	v_pk_mul_f32 v[102:103], v[68:69], v[88:89] op_sel_hi:[1,0]
	v_pk_mul_f32 v[82:83], v[94:95], v[82:83]
	v_mul_f32_e32 v101, 0xbfb8aa3b, v102
	v_exp_f32_e32 v104, v101
	v_mul_f32_e32 v101, 0xbfb8aa3b, v103
	v_exp_f32_e32 v105, v101
	v_rcp_f32_e32 v101, v89
	v_add_f32_e32 v89, 1.0, v104
	v_rcp_f32_e32 v104, v89
	v_add_f32_e32 v89, 1.0, v105
	v_rcp_f32_e32 v105, v89
	v_pk_mul_f32 v[84:85], v[84:85], v[96:97]
	v_pk_mul_f32 v[96:97], v[98:99], v[100:101]
	v_cvt_pk_bf16_f32 v82, v82, v83
	v_pk_mul_f32 v[94:95], v[102:103], v[104:105]
	v_cvt_pk_bf16_f32 v83, v84, v85
	v_cvt_pk_bf16_f32 v84, v96, v97

; __device__ __forceinline__ float silu_f(float x) { return x * __builtin_amdgcn_rcpf(1.0f + __expf(-x)); }
;     __device__ __forceinline__ void operator()(const Acc& acc, const pg8::Unit& u, int wr, int wc, int fr, int fq) const {
;     ...
;             for (int m = 0; m < 4; ++m) {
;                 const int row = u.pm * 256 + ai * 128 + wr * 64 + m * 16 + fr;
;                 const float rs = row_rs(part, row);
;                 if (u.pn < 8) {
;                     const int pidx = row < TP ? (row & (SEQ - 1)) : SEQ + ((row - TP) & 3);
;                     const int i0 = wc * 32 + 8 * fq;
;                     const f32x4* cs = (const f32x4*)(rope + ((size_t)pidx * 128 + i0) * 2);
;                     const float sc = (u.pn < 4) ? rs : rs * 0.0625f;
;                     f32x4 o1[2], o2[2];
; #pragma unroll
;                     for (int n = 0; n < 2; ++n) { const f32x4 c01 = cs[2 * n], c23 = cs[2 * n + 1];
;                         const f32x4 x1 = acc[ai][0][m][n] * sc, x2 = acc[ai][1][m][n] * sc;
;                         const f32x4 cc = (f32x4){c01[0], c01[2], c23[0], c23[2]}, sn = (f32x4){c01[1], c01[3], c23[1], c23[3]};
;                         o1[n] = x1 * cc - x2 * sn; o2[n] = x1 * sn + x2 * cc; }
;                     bf16_t* dst = (u.pn < 4 ? Q : K) + (size_t)row * D + (u.pn & 3) * 256 + i0;
;                     *(u32x4*)dst = pack8(o1[0], o1[1]); *(u32x4*)(dst + 128) = pack8(o2[0], o2[1]);
;                 } else if (u.pn < 16) {
; #pragma unroll
;                     for (int bj = 0; bj < 2; ++bj) { const int col = (u.pn - 8) * 256 + bj * 128 + wc * 32 + 8 * fq;
;                         *(u32x4*)(V + (size_t)row * VD + col) = pack8(acc[ai][bj][m][0] * rs, acc[ai][bj][m][1] * rs); }
;                 } else {
; #pragma unroll
;                     for (int bj = 0; bj < 2; ++bj) { const int col = (u.pn - 16) * 256 + bj * 128 + wc * 32 + 8 * fq;
;                         f32x4 g[2];
; #pragma unroll
;                         for (int n = 0; n < 2; ++n)
; #pragma unroll
;                             for (int e = 0; e < 4; ++e) g[n][e] = silu_f(acc[ai][bj][m][n][e] * rs);
;                         *(u32x4*)(G + (size_t)row * VD + col) = pack8(g[0], g[1]); }
.LBB0_869:
	v_add_u32_e32 v70, 0x80, v160
	v_ashrrev_i32_e32 v71, 31, v70
	v_cvt_pk_bf16_f32 v85, v94, v95
	v_lshlrev_b64 v[66:67], 6, v[70:71]
	global_store_dwordx4 v[90:91], v[82:85], off offset:256
	v_lshl_add_u64 v[80:81], s[90:91], 0, v[66:67]
	s_nop 0
	s_and_b64 vcc, exec, s[8:9]
	s_nop 0
	s_nop 0
	s_nop 1
	s_nop 0
	v_mov_b32_e32 v72, v202
	s_mov_b64 s[10:11], -1
	s_cbranch_vccnz .LBB0_875
	s_and_b64 vcc, exec, s[6:7]
	v_lshlrev_b64 v[76:77], 12, v[70:71]
	s_cbranch_vccnz .LBB0_872
	v_pk_mul_f32 v[74:75], v[64:65], v[72:73] op_sel_hi:[1,0]
	v_pk_mul_f32 v[66:67], v[62:63], v[72:73] op_sel_hi:[1,0]
	v_mul_f32_e32 v73, 0xbfb8aa3b, v74
	v_exp_f32_e32 v73, v73
	v_mul_f32_e32 v78, 0xbfb8aa3b, v75
	v_exp_f32_e32 v79, v78
	v_mul_f32_e32 v68, 0xbfb8aa3b, v66
	v_add_f32_e32 v73, 1.0, v73
	v_rcp_f32_e32 v78, v73
	v_add_f32_e32 v73, 1.0, v79
	v_pk_mul_f32 v[80:81], v[58:59], v[72:73] op_sel_hi:[1,0]
	v_mul_f32_e32 v69, 0xbfb8aa3b, v67
	v_mul_f32_e32 v79, 0xbfb8aa3b, v80
	v_exp_f32_e32 v82, v79
	v_mul_f32_e32 v79, 0xbfb8aa3b, v81
	v_exp_f32_e32 v83, v79
	v_rcp_f32_e32 v79, v73
	v_add_f32_e32 v73, 1.0, v82
	v_rcp_f32_e32 v82, v73
	v_add_f32_e32 v73, 1.0, v83
	v_pk_mul_f32 v[84:85], v[60:61], v[72:73] op_sel_hi:[1,0]
	v_exp_f32_e32 v68, v68
	v_mul_f32_e32 v83, 0xbfb8aa3b, v84
	v_exp_f32_e32 v86, v83
	v_mul_f32_e32 v83, 0xbfb8aa3b, v85
	v_exp_f32_e32 v69, v69
	v_exp_f32_e32 v87, v83
	v_rcp_f32_e32 v83, v73
	v_add_f32_e32 v73, 1.0, v86
	v_add_f32_e32 v68, 1.0, v68
	v_add_f32_e32 v69, 1.0, v69
	v_rcp_f32_e32 v86, v73
	v_add_f32_e32 v73, 1.0, v87
	v_rcp_f32_e32 v68, v68
	v_rcp_f32_e32 v69, v69
	v_rcp_f32_e32 v87, v73
	v_ashrrev_i32_e32 v157, 31, v156
	s_mov_b64 s[10:11], 0
	v_pk_mul_f32 v[66:67], v[66:67], v[68:69]
	v_pk_mul_f32 v[68:69], v[74:75], v[78:79]
	v_pk_mul_f32 v[78:79], v[84:85], v[86:87]
	v_cvt_pk_bf16_f32 v66, v66, v67
	v_cvt_pk_bf16_f32 v67, v68, v69
	v_cvt_pk_bf16_f32 v69, v78, v79
	v_pk_mul_f32 v[78:79], v[54:55], v[72:73] op_sel_hi:[1,0]
	v_pk_mul_f32 v[74:75], v[80:81], v[82:83]
	v_mul_f32_e32 v73, 0xbfb8aa3b, v78
	v_exp_f32_e32 v73, v73
	v_mul_f32_e32 v80, 0xbfb8aa3b, v79
	v_cvt_pk_bf16_f32 v68, v74, v75
	v_lshl_add_u64 v[74:75], s[22:23], 0, v[76:77]
	v_exp_f32_e32 v80, v80
	v_lshl_add_u64 v[74:75], v[156:157], 1, v[74:75]
	global_store_dwordx4 v[74:75], v[66:69], off
	s_nop 1
	v_pk_mul_f32 v[68:69], v[56:57], v[72:73] op_sel_hi:[1,0]
	v_add_f32_e32 v66, 1.0, v73
	v_mul_f32_e32 v73, 0xbfb8aa3b, v68
	v_add_f32_e32 v67, 1.0, v80
	v_exp_f32_e32 v73, v73
	v_mul_f32_e32 v80, 0xbfb8aa3b, v69
	v_exp_f32_e32 v81, v80
	v_rcp_f32_e32 v66, v66
	v_add_f32_e32 v73, 1.0, v73
	v_rcp_f32_e32 v80, v73
	v_add_f32_e32 v73, 1.0, v81
	v_pk_mul_f32 v[82:83], v[50:51], v[72:73] op_sel_hi:[1,0]
	v_rcp_f32_e32 v67, v67
	v_mul_f32_e32 v81, 0xbfb8aa3b, v82
	v_exp_f32_e32 v84, v81
	v_mul_f32_e32 v81, 0xbfb8aa3b, v83
	v_exp_f32_e32 v85, v81
	v_rcp_f32_e32 v81, v73
	v_add_f32_e32 v73, 1.0, v84
	v_rcp_f32_e32 v84, v73
	v_add_f32_e32 v73, 1.0, v85
	v_pk_mul_f32 v[86:87], v[52:53], v[72:73] op_sel_hi:[1,0]
	v_pk_mul_f32 v[66:67], v[78:79], v[66:67]
	v_mul_f32_e32 v85, 0xbfb8aa3b, v86
	v_exp_f32_e32 v88, v85
	v_mul_f32_e32 v85, 0xbfb8aa3b, v87
	v_exp_f32_e32 v89, v85
	v_rcp_f32_e32 v85, v73
	v_add_f32_e32 v73, 1.0, v88
	v_rcp_f32_e32 v88, v73
	v_add_f32_e32 v73, 1.0, v89
	v_rcp_f32_e32 v89, v73
	v_pk_mul_f32 v[68:69], v[68:69], v[80:81]
	v_pk_mul_f32 v[80:81], v[82:83], v[84:85]
	v_cvt_pk_bf16_f32 v66, v66, v67
	v_pk_mul_f32 v[78:79], v[86:87], v[88:89]
	v_cvt_pk_bf16_f32 v67, v68, v69
	v_cvt_pk_bf16_f32 v68, v80, v81

; __device__ __forceinline__ float silu_f(float x) { return x * __builtin_amdgcn_rcpf(1.0f + __expf(-x)); }
;     __device__ __forceinline__ void operator()(const Acc& acc, const pg8::Unit& u, int wr, int wc, int fr, int fq) const {
;     ...
;             for (int m = 0; m < 4; ++m) {
;                 const int row = u.pm * 256 + ai * 128 + wr * 64 + m * 16 + fr;
;                 const float rs = row_rs(part, row);
;                 if (u.pn < 8) {
;                     const int pidx = row < TP ? (row & (SEQ - 1)) : SEQ + ((row - TP) & 3);
;                     const int i0 = wc * 32 + 8 * fq;
;                     const f32x4* cs = (const f32x4*)(rope + ((size_t)pidx * 128 + i0) * 2);
;                     const float sc = (u.pn < 4) ? rs : rs * 0.0625f;
;                     f32x4 o1[2], o2[2];
; #pragma unroll
;                     for (int n = 0; n < 2; ++n) { const f32x4 c01 = cs[2 * n], c23 = cs[2 * n + 1];
;                         const f32x4 x1 = acc[ai][0][m][n] * sc, x2 = acc[ai][1][m][n] * sc;
;                         const f32x4 cc = (f32x4){c01[0], c01[2], c23[0], c23[2]}, sn = (f32x4){c01[1], c01[3], c23[1], c23[3]};
;                         o1[n] = x1 * cc - x2 * sn; o2[n] = x1 * sn + x2 * cc; }
;                     bf16_t* dst = (u.pn < 4 ? Q : K) + (size_t)row * D + (u.pn & 3) * 256 + i0;
;                     *(u32x4*)dst = pack8(o1[0], o1[1]); *(u32x4*)(dst + 128) = pack8(o2[0], o2[1]);
;                 } else if (u.pn < 16) {
; #pragma unroll
;                     for (int bj = 0; bj < 2; ++bj) { const int col = (u.pn - 8) * 256 + bj * 128 + wc * 32 + 8 * fq;
;                         *(u32x4*)(V + (size_t)row * VD + col) = pack8(acc[ai][bj][m][0] * rs, acc[ai][bj][m][1] * rs); }
;                 } else {
; #pragma unroll
;                     for (int bj = 0; bj < 2; ++bj) { const int col = (u.pn - 16) * 256 + bj * 128 + wc * 32 + 8 * fq;
;                         f32x4 g[2];
; #pragma unroll
;                         for (int n = 0; n < 2; ++n)
; #pragma unroll
;                             for (int e = 0; e < 4; ++e) g[n][e] = silu_f(acc[ai][bj][m][n][e] * rs);
;                         *(u32x4*)(G + (size_t)row * VD + col) = pack8(g[0], g[1]); }
.LBB0_877:
	v_add_u32_e32 v54, 0x90, v160
	v_ashrrev_i32_e32 v55, 31, v54
	v_cvt_pk_bf16_f32 v69, v78, v79
	v_lshlrev_b64 v[50:51], 6, v[54:55]
	global_store_dwordx4 v[74:75], v[66:69], off offset:256
	v_lshl_add_u64 v[64:65], s[90:91], 0, v[50:51]
	s_nop 0
	s_and_b64 vcc, exec, s[8:9]
	s_nop 0
	s_nop 0
	s_nop 1
	s_nop 0
	v_mov_b32_e32 v56, v203
	s_mov_b64 s[10:11], -1
	s_cbranch_vccnz .LBB0_883
	s_and_b64 vcc, exec, s[6:7]
	v_lshlrev_b64 v[60:61], 12, v[54:55]
	s_cbranch_vccnz .LBB0_880
	v_pk_mul_f32 v[58:59], v[48:49], v[56:57] op_sel_hi:[1,0]
	v_pk_mul_f32 v[50:51], v[46:47], v[56:57] op_sel_hi:[1,0]
	v_mul_f32_e32 v57, 0xbfb8aa3b, v58
	v_exp_f32_e32 v57, v57
	v_mul_f32_e32 v62, 0xbfb8aa3b, v59
	v_exp_f32_e32 v63, v62
	v_mul_f32_e32 v52, 0xbfb8aa3b, v50
	v_add_f32_e32 v57, 1.0, v57
	v_rcp_f32_e32 v62, v57
	v_add_f32_e32 v57, 1.0, v63
	v_pk_mul_f32 v[64:65], v[42:43], v[56:57] op_sel_hi:[1,0]
	v_mul_f32_e32 v53, 0xbfb8aa3b, v51
	v_mul_f32_e32 v63, 0xbfb8aa3b, v64
	v_exp_f32_e32 v66, v63
	v_mul_f32_e32 v63, 0xbfb8aa3b, v65
	v_exp_f32_e32 v67, v63
	v_rcp_f32_e32 v63, v57
	v_add_f32_e32 v57, 1.0, v66
	v_rcp_f32_e32 v66, v57
	v_add_f32_e32 v57, 1.0, v67
	v_pk_mul_f32 v[68:69], v[44:45], v[56:57] op_sel_hi:[1,0]
	v_exp_f32_e32 v52, v52
	v_mul_f32_e32 v67, 0xbfb8aa3b, v68
	v_exp_f32_e32 v70, v67
	v_mul_f32_e32 v67, 0xbfb8aa3b, v69
	v_exp_f32_e32 v53, v53
	v_exp_f32_e32 v71, v67
	v_rcp_f32_e32 v67, v57
	v_add_f32_e32 v57, 1.0, v70
	v_add_f32_e32 v52, 1.0, v52
	v_add_f32_e32 v53, 1.0, v53
	v_rcp_f32_e32 v70, v57
	v_add_f32_e32 v57, 1.0, v71
	v_rcp_f32_e32 v52, v52
	v_rcp_f32_e32 v53, v53
	v_rcp_f32_e32 v71, v57
	v_ashrrev_i32_e32 v157, 31, v156
	s_mov_b64 s[10:11], 0
	v_pk_mul_f32 v[50:51], v[50:51], v[52:53]
	v_pk_mul_f32 v[52:53], v[58:59], v[62:63]
	v_pk_mul_f32 v[62:63], v[68:69], v[70:71]
	v_cvt_pk_bf16_f32 v50, v50, v51
	v_cvt_pk_bf16_f32 v51, v52, v53
	v_cvt_pk_bf16_f32 v53, v62, v63
	v_pk_mul_f32 v[62:63], v[38:39], v[56:57] op_sel_hi:[1,0]
	v_pk_mul_f32 v[58:59], v[64:65], v[66:67]
	v_mul_f32_e32 v57, 0xbfb8aa3b, v62
	v_exp_f32_e32 v57, v57
	v_mul_f32_e32 v64, 0xbfb8aa3b, v63
	v_cvt_pk_bf16_f32 v52, v58, v59
	v_lshl_add_u64 v[58:59], s[22:23], 0, v[60:61]
	v_exp_f32_e32 v64, v64
	v_lshl_add_u64 v[58:59], v[156:157], 1, v[58:59]
	global_store_dwordx4 v[58:59], v[50:53], off
	s_nop 1
	v_pk_mul_f32 v[52:53], v[40:41], v[56:57] op_sel_hi:[1,0]
	v_add_f32_e32 v50, 1.0, v57
	v_mul_f32_e32 v57, 0xbfb8aa3b, v52
	v_add_f32_e32 v51, 1.0, v64
	v_exp_f32_e32 v57, v57
	v_mul_f32_e32 v64, 0xbfb8aa3b, v53
	v_exp_f32_e32 v65, v64
	v_rcp_f32_e32 v50, v50
	v_add_f32_e32 v57, 1.0, v57
	v_rcp_f32_e32 v64, v57
	v_add_f32_e32 v57, 1.0, v65
	v_pk_mul_f32 v[66:67], v[34:35], v[56:57] op_sel_hi:[1,0]
	v_rcp_f32_e32 v51, v51
	v_mul_f32_e32 v65, 0xbfb8aa3b, v66
	v_exp_f32_e32 v68, v65
	v_mul_f32_e32 v65, 0xbfb8aa3b, v67
	v_exp_f32_e32 v69, v65
	v_rcp_f32_e32 v65, v57
	v_add_f32_e32 v57, 1.0, v68
	v_rcp_f32_e32 v68, v57
	v_add_f32_e32 v57, 1.0, v69
	v_pk_mul_f32 v[70:71], v[36:37], v[56:57] op_sel_hi:[1,0]
	v_pk_mul_f32 v[50:51], v[62:63], v[50:51]
	v_mul_f32_e32 v69, 0xbfb8aa3b, v70
	v_exp_f32_e32 v72, v69
	v_mul_f32_e32 v69, 0xbfb8aa3b, v71
	v_exp_f32_e32 v73, v69
	v_rcp_f32_e32 v69, v57
	v_add_f32_e32 v57, 1.0, v72
	v_rcp_f32_e32 v72, v57
	v_add_f32_e32 v57, 1.0, v73
	v_rcp_f32_e32 v73, v57
	v_pk_mul_f32 v[52:53], v[52:53], v[64:65]
	v_pk_mul_f32 v[64:65], v[66:67], v[68:69]
	v_cvt_pk_bf16_f32 v50, v50, v51
	v_pk_mul_f32 v[62:63], v[70:71], v[72:73]
	v_cvt_pk_bf16_f32 v51, v52, v53
	v_cvt_pk_bf16_f32 v52, v64, v65

; __device__ __forceinline__ float row_rs(const float* part, int row) {
;     const f32x4* p = (const f32x4*)(part + (size_t)row * 16);
;     const f32x4 a = p[0], b = p[1], c = p[2], d = p[3];
;     __device__ __forceinline__ void operator()(const Acc& acc, const pg8::Unit& u, int wr, int wc, int fr, int fq) const {
;     ...
;             for (int m = 0; m < 4; ++m) {
;                 const int row = u.pm * 256 + ai * 128 + wr * 64 + m * 16 + fr;
;                 const float rs = row_rs(part, row);
;                 if (u.pn < 8) {
;                     const int pidx = row < TP ? (row & (SEQ - 1)) : SEQ + ((row - TP) & 3);
;                     const int i0 = wc * 32 + 8 * fq;
;                     const f32x4* cs = (const f32x4*)(rope + ((size_t)pidx * 128 + i0) * 2);
;                     const float sc = (u.pn < 4) ? rs : rs * 0.0625f;
;                     f32x4 o1[2], o2[2];
; #pragma unroll
;                     for (int n = 0; n < 2; ++n) { const f32x4 c01 = cs[2 * n], c23 = cs[2 * n + 1];
;                         const f32x4 x1 = acc[ai][0][m][n] * sc, x2 = acc[ai][1][m][n] * sc;
;                         const f32x4 cc = (f32x4){c01[0], c01[2], c23[0], c23[2]}, sn = (f32x4){c01[1], c01[3], c23[1], c23[3]};
;                         o1[n] = x1 * cc - x2 * sn; o2[n] = x1 * sn + x2 * cc; }
;                     bf16_t* dst = (u.pn < 4 ? Q : K) + (size_t)row * D + (u.pn & 3) * 256 + i0;
;                     *(u32x4*)dst = pack8(o1[0], o1[1]); *(u32x4*)(dst + 128) = pack8(o2[0], o2[1]);
;                 } else if (u.pn < 16) {
; #pragma unroll
;                     for (int bj = 0; bj < 2; ++bj) { const int col = (u.pn - 8) * 256 + bj * 128 + wc * 32 + 8 * fq;
;                         *(u32x4*)(V + (size_t)row * VD + col) = pack8(acc[ai][bj][m][0] * rs, acc[ai][bj][m][1] * rs); }
;                 } else {
; #pragma unroll
;                     for (int bj = 0; bj < 2; ++bj) { const int col = (u.pn - 16) * 256 + bj * 128 + wc * 32 + 8 * fq;
;                         f32x4 g[2];
; #pragma unroll
;                         for (int n = 0; n < 2; ++n)
; #pragma unroll
;                             for (int e = 0; e < 4; ++e) g[n][e] = silu_f(acc[ai][bj][m][n][e] * rs);
;                         *(u32x4*)(G + (size_t)row * VD + col) = pack8(g[0], g[1]); }
.LBB0_885:
	v_add_u32_e32 v38, 0xa0, v160
	v_ashrrev_i32_e32 v39, 31, v38
	v_cvt_pk_bf16_f32 v53, v62, v63
	v_lshlrev_b64 v[34:35], 6, v[38:39]
	global_store_dwordx4 v[58:59], v[50:53], off offset:256
	v_lshl_add_u64 v[48:49], s[90:91], 0, v[34:35]
	s_nop 0
	s_and_b64 vcc, exec, s[8:9]
	s_nop 0
	s_nop 0
	s_nop 1
	s_nop 0
	s_waitcnt vmcnt(6)
	v_add_f32_e32 v190, v190, v191
	v_add_f32_e32 v192, v192, v193
	v_add_f32_e32 v194, v194, v195
	v_add_f32_e32 v196, v196, v197
	v_add_f32_e32 v204, v190, v192
	v_add_f32_e32 v205, v194, v196
	v_mov_b32_e32 v212, v204
	v_mov_b32_e32 v213, v205
	s_nop 1
	v_permlane16_swap_b32_e32 v204, v212
	v_permlane16_swap_b32_e32 v205, v213
	v_add_f32_e32 v204, v204, v212
	v_add_f32_e32 v205, v205, v213
	v_mov_b32_e32 v212, v204
	v_mov_b32_e32 v213, v205
	s_nop 1
	v_permlane32_swap_b32_e32 v204, v212
	v_permlane32_swap_b32_e32 v205, v213
	v_add_f32_e32 v204, v204, v212
	v_add_f32_e32 v205, v205, v213
	v_fmamk_f32 v204, v204, 0x3a800000, v171
	v_fmamk_f32 v205, v205, 0x3a800000, v171
	v_rsq_f32_e32 v204, v204
	v_rsq_f32_e32 v205, v205
	v_mov_b32_e32 v40, v204
	s_mov_b64 s[10:11], -1
	s_cbranch_vccnz .LBB0_891
	s_and_b64 vcc, exec, s[6:7]
	v_lshlrev_b64 v[44:45], 12, v[38:39]
	s_cbranch_vccnz .LBB0_888
	v_pk_mul_f32 v[42:43], v[32:33], v[40:41] op_sel_hi:[1,0]
	v_pk_mul_f32 v[34:35], v[30:31], v[40:41] op_sel_hi:[1,0]
	v_mul_f32_e32 v41, 0xbfb8aa3b, v42
	v_exp_f32_e32 v41, v41
	v_mul_f32_e32 v46, 0xbfb8aa3b, v43
	v_exp_f32_e32 v47, v46
	v_mul_f32_e32 v36, 0xbfb8aa3b, v34
	v_add_f32_e32 v41, 1.0, v41
	v_rcp_f32_e32 v46, v41
	v_add_f32_e32 v41, 1.0, v47
	v_pk_mul_f32 v[48:49], v[26:27], v[40:41] op_sel_hi:[1,0]
	v_mul_f32_e32 v37, 0xbfb8aa3b, v35
	v_mul_f32_e32 v47, 0xbfb8aa3b, v48
	v_exp_f32_e32 v50, v47
	v_mul_f32_e32 v47, 0xbfb8aa3b, v49
	v_exp_f32_e32 v51, v47
	v_rcp_f32_e32 v47, v41
	v_add_f32_e32 v41, 1.0, v50
	v_rcp_f32_e32 v50, v41
	v_add_f32_e32 v41, 1.0, v51
	v_pk_mul_f32 v[52:53], v[28:29], v[40:41] op_sel_hi:[1,0]
	v_exp_f32_e32 v36, v36
	v_mul_f32_e32 v51, 0xbfb8aa3b, v52
	v_exp_f32_e32 v54, v51
	v_mul_f32_e32 v51, 0xbfb8aa3b, v53
	v_exp_f32_e32 v37, v37
	v_exp_f32_e32 v55, v51
	v_rcp_f32_e32 v51, v41
	v_add_f32_e32 v41, 1.0, v54
	v_add_f32_e32 v36, 1.0, v36
	v_add_f32_e32 v37, 1.0, v37
	v_rcp_f32_e32 v54, v41
	v_add_f32_e32 v41, 1.0, v55
	v_rcp_f32_e32 v36, v36
	v_rcp_f32_e32 v37, v37
	v_rcp_f32_e32 v55, v41
	v_ashrrev_i32_e32 v157, 31, v156
	s_mov_b64 s[10:11], 0
	v_pk_mul_f32 v[34:35], v[34:35], v[36:37]
	v_pk_mul_f32 v[36:37], v[42:43], v[46:47]
	v_pk_mul_f32 v[46:47], v[52:53], v[54:55]
	v_cvt_pk_bf16_f32 v34, v34, v35
	v_cvt_pk_bf16_f32 v35, v36, v37
	v_cvt_pk_bf16_f32 v37, v46, v47
	v_pk_mul_f32 v[46:47], v[22:23], v[40:41] op_sel_hi:[1,0]
	v_pk_mul_f32 v[42:43], v[48:49], v[50:51]
	v_mul_f32_e32 v41, 0xbfb8aa3b, v46
	v_exp_f32_e32 v41, v41
	v_mul_f32_e32 v48, 0xbfb8aa3b, v47
	v_cvt_pk_bf16_f32 v36, v42, v43
	v_lshl_add_u64 v[42:43], s[22:23], 0, v[44:45]
	v_exp_f32_e32 v48, v48
	v_lshl_add_u64 v[42:43], v[156:157], 1, v[42:43]
	global_store_dwordx4 v[42:43], v[34:37], off
	s_nop 1
	v_pk_mul_f32 v[36:37], v[24:25], v[40:41] op_sel_hi:[1,0]
	v_add_f32_e32 v34, 1.0, v41
	v_mul_f32_e32 v41, 0xbfb8aa3b, v36
	v_add_f32_e32 v35, 1.0, v48
	v_exp_f32_e32 v41, v41
	v_mul_f32_e32 v48, 0xbfb8aa3b, v37
	v_exp_f32_e32 v49, v48
	v_rcp_f32_e32 v34, v34
	v_add_f32_e32 v41, 1.0, v41
	v_rcp_f32_e32 v48, v41
	v_add_f32_e32 v41, 1.0, v49
	v_pk_mul_f32 v[50:51], v[18:19], v[40:41] op_sel_hi:[1,0]
	v_rcp_f32_e32 v35, v35
	v_mul_f32_e32 v49, 0xbfb8aa3b, v50
	v_exp_f32_e32 v52, v49
	v_mul_f32_e32 v49, 0xbfb8aa3b, v51
	v_exp_f32_e32 v53, v49
	v_rcp_f32_e32 v49, v41
	v_add_f32_e32 v41, 1.0, v52
	v_rcp_f32_e32 v52, v41
	v_add_f32_e32 v41, 1.0, v53
	v_pk_mul_f32 v[54:55], v[20:21], v[40:41] op_sel_hi:[1,0]
	v_pk_mul_f32 v[34:35], v[46:47], v[34:35]
	v_mul_f32_e32 v53, 0xbfb8aa3b, v54
	v_exp_f32_e32 v56, v53
	v_mul_f32_e32 v53, 0xbfb8aa3b, v55
	v_exp_f32_e32 v57, v53
	v_rcp_f32_e32 v53, v41
	v_add_f32_e32 v41, 1.0, v56
	v_rcp_f32_e32 v56, v41
	v_add_f32_e32 v41, 1.0, v57
	v_rcp_f32_e32 v57, v41
	v_pk_mul_f32 v[36:37], v[36:37], v[48:49]
	v_pk_mul_f32 v[48:49], v[50:51], v[52:53]
	v_cvt_pk_bf16_f32 v34, v34, v35
	v_pk_mul_f32 v[46:47], v[54:55], v[56:57]
	v_cvt_pk_bf16_f32 v35, v36, v37
	v_cvt_pk_bf16_f32 v36, v48, v49

; __device__ __forceinline__ float silu_f(float x) { return x * __builtin_amdgcn_rcpf(1.0f + __expf(-x)); }
;     __device__ __forceinline__ void operator()(const Acc& acc, const pg8::Unit& u, int wr, int wc, int fr, int fq) const {
;     ...
;             for (int m = 0; m < 4; ++m) {
;                 const int row = u.pm * 256 + ai * 128 + wr * 64 + m * 16 + fr;
;                 const float rs = row_rs(part, row);
;                 if (u.pn < 8) {
;                     const int pidx = row < TP ? (row & (SEQ - 1)) : SEQ + ((row - TP) & 3);
;                     const int i0 = wc * 32 + 8 * fq;
;                     const f32x4* cs = (const f32x4*)(rope + ((size_t)pidx * 128 + i0) * 2);
;                     const float sc = (u.pn < 4) ? rs : rs * 0.0625f;
;                     f32x4 o1[2], o2[2];
; #pragma unroll
;                     for (int n = 0; n < 2; ++n) { const f32x4 c01 = cs[2 * n], c23 = cs[2 * n + 1];
;                         const f32x4 x1 = acc[ai][0][m][n] * sc, x2 = acc[ai][1][m][n] * sc;
;                         const f32x4 cc = (f32x4){c01[0], c01[2], c23[0], c23[2]}, sn = (f32x4){c01[1], c01[3], c23[1], c23[3]};
;                         o1[n] = x1 * cc - x2 * sn; o2[n] = x1 * sn + x2 * cc; }
;                     bf16_t* dst = (u.pn < 4 ? Q : K) + (size_t)row * D + (u.pn & 3) * 256 + i0;
;                     *(u32x4*)dst = pack8(o1[0], o1[1]); *(u32x4*)(dst + 128) = pack8(o2[0], o2[1]);
;                 } else if (u.pn < 16) {
; #pragma unroll
;                     for (int bj = 0; bj < 2; ++bj) { const int col = (u.pn - 8) * 256 + bj * 128 + wc * 32 + 8 * fq;
;                         *(u32x4*)(V + (size_t)row * VD + col) = pack8(acc[ai][bj][m][0] * rs, acc[ai][bj][m][1] * rs); }
;                 } else {
; #pragma unroll
;                     for (int bj = 0; bj < 2; ++bj) { const int col = (u.pn - 16) * 256 + bj * 128 + wc * 32 + 8 * fq;
;                         f32x4 g[2];
; #pragma unroll
;                         for (int n = 0; n < 2; ++n)
; #pragma unroll
;                             for (int e = 0; e < 4; ++e) g[n][e] = silu_f(acc[ai][bj][m][n][e] * rs);
;                         *(u32x4*)(G + (size_t)row * VD + col) = pack8(g[0], g[1]); }
.LBB0_893:
	v_add_u32_e32 v22, 0xb0, v160
	v_ashrrev_i32_e32 v23, 31, v22
	v_cvt_pk_bf16_f32 v37, v46, v47
	v_lshlrev_b64 v[18:19], 6, v[22:23]
	global_store_dwordx4 v[42:43], v[34:37], off offset:256
	v_lshl_add_u64 v[32:33], s[90:91], 0, v[18:19]
	s_nop 0
	s_and_b64 vcc, exec, s[8:9]
	s_mov_b64 s[8:9], -1
	s_nop 0
	s_nop 0
	s_nop 1
	s_nop 0
	v_mov_b32_e32 v24, v205
	s_cbranch_vccnz .LBB0_899
	s_and_b64 vcc, exec, s[6:7]
	v_lshlrev_b64 v[28:29], 12, v[22:23]
	s_cbranch_vccnz .LBB0_896
	v_pk_mul_f32 v[26:27], v[16:17], v[24:25] op_sel_hi:[1,0]
	v_pk_mul_f32 v[18:19], v[14:15], v[24:25] op_sel_hi:[1,0]
	v_mul_f32_e32 v25, 0xbfb8aa3b, v26
	v_exp_f32_e32 v25, v25
	v_mul_f32_e32 v30, 0xbfb8aa3b, v27
	v_exp_f32_e32 v31, v30
	v_mul_f32_e32 v20, 0xbfb8aa3b, v18
	v_add_f32_e32 v25, 1.0, v25
	v_rcp_f32_e32 v30, v25
	v_add_f32_e32 v25, 1.0, v31
	v_pk_mul_f32 v[32:33], v[10:11], v[24:25] op_sel_hi:[1,0]
	v_mul_f32_e32 v21, 0xbfb8aa3b, v19
	v_mul_f32_e32 v31, 0xbfb8aa3b, v32
	v_exp_f32_e32 v34, v31
	v_mul_f32_e32 v31, 0xbfb8aa3b, v33
	v_exp_f32_e32 v35, v31
	v_rcp_f32_e32 v31, v25
	v_add_f32_e32 v25, 1.0, v34
	v_rcp_f32_e32 v34, v25
	v_add_f32_e32 v25, 1.0, v35
	v_pk_mul_f32 v[36:37], v[12:13], v[24:25] op_sel_hi:[1,0]
	v_exp_f32_e32 v20, v20
	v_mul_f32_e32 v35, 0xbfb8aa3b, v36
	v_exp_f32_e32 v38, v35
	v_mul_f32_e32 v35, 0xbfb8aa3b, v37
	v_exp_f32_e32 v21, v21
	v_exp_f32_e32 v39, v35
	v_rcp_f32_e32 v35, v25
	v_add_f32_e32 v25, 1.0, v38
	v_add_f32_e32 v20, 1.0, v20
	v_add_f32_e32 v21, 1.0, v21
	v_rcp_f32_e32 v38, v25
	v_add_f32_e32 v25, 1.0, v39
	v_rcp_f32_e32 v20, v20
	v_rcp_f32_e32 v21, v21
	v_rcp_f32_e32 v39, v25
	v_ashrrev_i32_e32 v157, 31, v156
	s_mov_b64 s[8:9], 0
	v_pk_mul_f32 v[18:19], v[18:19], v[20:21]
	v_pk_mul_f32 v[20:21], v[26:27], v[30:31]
	v_pk_mul_f32 v[30:31], v[36:37], v[38:39]
	v_cvt_pk_bf16_f32 v18, v18, v19
	v_cvt_pk_bf16_f32 v19, v20, v21
	v_cvt_pk_bf16_f32 v21, v30, v31
	v_pk_mul_f32 v[30:31], v[6:7], v[24:25] op_sel_hi:[1,0]
	v_pk_mul_f32 v[26:27], v[32:33], v[34:35]
	v_mul_f32_e32 v25, 0xbfb8aa3b, v30
	v_exp_f32_e32 v25, v25
	v_mul_f32_e32 v32, 0xbfb8aa3b, v31
	v_cvt_pk_bf16_f32 v20, v26, v27
	v_lshl_add_u64 v[26:27], s[22:23], 0, v[28:29]
	v_exp_f32_e32 v32, v32
	v_lshl_add_u64 v[26:27], v[156:157], 1, v[26:27]
	global_store_dwordx4 v[26:27], v[18:21], off
	s_nop 1
	v_pk_mul_f32 v[20:21], v[8:9], v[24:25] op_sel_hi:[1,0]
	v_add_f32_e32 v18, 1.0, v25
	v_mul_f32_e32 v25, 0xbfb8aa3b, v20
	v_add_f32_e32 v19, 1.0, v32
	v_exp_f32_e32 v25, v25
	v_mul_f32_e32 v32, 0xbfb8aa3b, v21
	v_exp_f32_e32 v33, v32
	v_rcp_f32_e32 v18, v18
	v_add_f32_e32 v25, 1.0, v25
	v_rcp_f32_e32 v32, v25
	v_add_f32_e32 v25, 1.0, v33
	v_pk_mul_f32 v[34:35], v[2:3], v[24:25] op_sel_hi:[1,0]
	v_rcp_f32_e32 v19, v19
	v_mul_f32_e32 v33, 0xbfb8aa3b, v34
	v_exp_f32_e32 v36, v33
	v_mul_f32_e32 v33, 0xbfb8aa3b, v35
	v_exp_f32_e32 v37, v33
	v_rcp_f32_e32 v33, v25
	v_add_f32_e32 v25, 1.0, v36
	v_rcp_f32_e32 v36, v25
	v_add_f32_e32 v25, 1.0, v37
	v_pk_mul_f32 v[38:39], v[4:5], v[24:25] op_sel_hi:[1,0]
	v_pk_mul_f32 v[18:19], v[30:31], v[18:19]
	v_mul_f32_e32 v37, 0xbfb8aa3b, v38
	v_exp_f32_e32 v40, v37
	v_mul_f32_e32 v37, 0xbfb8aa3b, v39
	v_exp_f32_e32 v41, v37
	v_rcp_f32_e32 v37, v25
	v_add_f32_e32 v25, 1.0, v40
	v_rcp_f32_e32 v40, v25
	v_add_f32_e32 v25, 1.0, v41
	v_rcp_f32_e32 v41, v25
	v_pk_mul_f32 v[20:21], v[20:21], v[32:33]
	v_pk_mul_f32 v[32:33], v[34:35], v[36:37]
	v_cvt_pk_bf16_f32 v18, v18, v19
	v_pk_mul_f32 v[30:31], v[38:39], v[40:41]
	v_cvt_pk_bf16_f32 v19, v20, v21
	v_cvt_pk_bf16_f32 v20, v32, v33

; __device__ __forceinline__ void retention_fused(const Params& p, LAS unsigned char* lds, int unit) {
;     ...
;     for (int c = 0; c < 16; ++c) {
;         __syncthreads();
;         if ((c & 7) == 0) {
;             const int su = unit + (c >> 3) * 256, ss = su >> 2, sh = su & 3, t0 = TP + ss * 4;
;             const bf16_t* Qs = (const bf16_t*)(ws + WS_Q) + (size_t)t0 * D + sh * 256;
;             const bf16_t* Kq = (const bf16_t*)(ws + WS_K) + (size_t)t0 * D + sh * 256;
;             const bf16_t* Vq = (const bf16_t*)(ws + WS_V) + (size_t)t0 * VD + sh * 512;
;             Ogs = (bf16_t*)(ws + WS_O) + (size_t)t0 * VD + sh * 512;
;             sg = 1.0f - exp2f(-5.0f - (float)sh); sg2 = sg * sg; sg3 = sg2 * sg; sg4 = sg2 * sg2;
;             if (tid < 256) { const int d = tid;
;                 qs[d] = (f32x4){bf2f(Qs[d]), bf2f(Qs[D + d]), bf2f(Qs[2 * D + d]), bf2f(Qs[3 * D + d])};
;                 kws[d] = (f32x4){sg3 * bf2f(Kq[d]), sg2 * bf2f(Kq[D + d]), sg * bf2f(Kq[2 * D + d]), bf2f(Kq[3 * D + d])}; }
.LBB0_1038:
	s_and_b32 s58, s57, 7
	s_cmp_lg_u32 s58, 0
	s_barrier
	s_cbranch_scc1 .LBB0_1046
	s_lshl_b32 s23, s57, 5
	s_add_i32 s26, s23, s78
	s_and_b32 s23, s26, -4
	s_add_i32 s24, s23, 0x4000
	s_ashr_i32 s25, s24, 31
	s_lshl_b64 s[28:29], s[24:25], 11
	s_add_u32 s30, s38, s28
	s_addc_u32 s31, s39, s29
	s_add_u32 s28, s40, s28
	s_addc_u32 s29, s41, s29
	s_and_saveexec_b64 s[34:35], s[0:1]
	s_cbranch_execz .LBB0_1041
	global_load_ushort v34, v205, s[30:31]
	global_load_ushort v35, v205, s[30:31] offset:2048
	global_load_ushort v36, v206, s[30:31]
	global_load_ushort v37, v207, s[30:31]
	global_load_ushort v40, v207, s[28:29]
	global_load_ushort v41, v206, s[28:29]
	global_load_ushort v38, v205, s[28:29] offset:2048
	global_load_ushort v42, v205, s[28:29]
	s_waitcnt vmcnt(7)
	v_lshlrev_b32_e32 v34, 16, v34
	s_waitcnt vmcnt(6)
	v_lshlrev_b32_e32 v35, 16, v35
	s_waitcnt vmcnt(5)
	v_lshlrev_b32_e32 v36, 16, v36
	s_waitcnt vmcnt(4)
	v_lshlrev_b32_e32 v37, 16, v37
	ds_write_b128 v187, v[34:37]
	s_waitcnt vmcnt(2)
	v_lshlrev_b32_e32 v41, 16, v41
	s_waitcnt vmcnt(1)
	v_lshlrev_b32_e32 v39, 16, v38
	s_waitcnt vmcnt(0)
	v_lshlrev_b32_e32 v38, 16, v42
	v_pk_mul_f32 v[34:35], v[132:133], v[38:39]
	v_mul_f32_e32 v36, v131, v41
	v_lshlrev_b32_e32 v37, 16, v40
	ds_write_b128 v188, v[34:37]
